# v6 plus fused K-loop waits, redundant post-barrier wait removed, and no grid barrier between hgrn_h3 and the GLU GEMM (independent phases)
# baseline (speedup 1.0000x reference)
; #define INP(i) ((const float*)(const GASP float*)kargs()[(i)])
; __device__ __forceinline__ void conv_slot(const Frame& F, int l, int slot, int first_idle, int ipw) { conv_slot_rank(F, l, slot, F.bx >= first_idle ? F.bx - first_idle : -1, 256 - first_idle, ipw); }
; #define GEMM_CALL(EpiT, OrdT, E, Aptr, Bptr, LDA, LDB, KK, NM, NN) do { pg8::Gemm g_{(const pg8::bf16_t*)(Aptr), (const pg8::bf16_t*)(Bptr), (LDA), (LDB), (KK)}; OrdT S_; S_.init((NM), (NN), F.G, F.bx); \
;     pg8::gemm_phase<EpiT, OrdT, true, true>(F.lds, g_, S_, (E), F.tid); } while (0)
; #define PH_BEGIN if (ph >= lo && ph < hi) { const Frame F = make_frame(lds, wid); unsigned char* const ws = WSP;
; #define PH_END } if (ph >= lo && ph + 1 < hi) xcd_barrier(bar); ++ph;
; __global__ void __launch_bounds__(NTHR, 2) fwd_kernel(Args a_unused) {
;     ...
;                     PH_BEGIN hgrn_h3(F, j); PH_END
;                     PH_BEGIN { EpiGlu E{(bf16*)(ws + WS_MIX), (const bf16*)(ws + WS_YA), INP(I_BGLU) + j * 1024}; GEMM_CALL(EpiGlu, pg8::StaticOrder, E, ws + WS_YA, ws + WS_WGLU + (size_t)j * 1024 * 1024 * 2, 1024, 1024, 1024, NPAN, 4); conv_slot(F, l, 2, 132, 3); } PH_END
.LBB0_1815:
	v_readlane_b32 s6, v247, 38
	s_add_i32 s6, s6, 5
	s_cmp_lt_i32 s6, s81
	s_cselect_b64 s[26:27], -1, 0
	s_and_b64 s[2:3], s[2:3], s[26:27]
	s_andn2_b64 vcc, exec, s[2:3]
	s_branch .LBB0_1871
	s_waitcnt vmcnt(0)
	s_and_b64 vcc, exec, s[4:5]
	s_waitcnt vmcnt(0)
	s_barrier
	s_cbranch_vccnz .LBB0_1870
	v_cmp_eq_u32_e32 vcc, 0, v214
	s_and_saveexec_b64 s[2:3], vcc
	s_cbranch_execz .LBB0_1869
	v_readlane_b32 s11, v247, 49
	s_waitcnt vmcnt(0) expcnt(0) lgkmcnt(0)
	s_nop 0
	v_mov_b32_e32 v0, s11
	ds_read_b32 v2, v0
	v_readlane_b32 s11, v247, 50
	s_waitcnt lgkmcnt(0)
	v_cmp_ne_u32_e32 vcc, 0, v2
	v_mov_b32_e32 v0, s11
	ds_read_b32 v0, v0
	s_cbranch_vccnz .LBB0_1833
	v_readlane_b32 s16, v248, 2
	v_readlane_b32 s17, v248, 3
	s_load_dwordx2 s[12:13], s[16:17], 0x0
	s_load_dword s11, s[16:17], 0x8
	s_waitcnt lgkmcnt(0)
	s_mul_i32 s12, s13, s12
	s_mul_i32 s11, s12, s11
	s_mov_b32 s12, 1
	s_branch .LBB0_1821
